# cache policy: non-temporal hint on the LayerNorm next-row streaming loads (three row loops)
# baseline (speedup 1.0000x reference)
.LBB0_1624:
	s_add_i32 s7, s6, s82
	s_cmpk_gt_i32 s7, 0x7fff
	s_cselect_b64 s[2:3], -1, 0
	s_cmp_lt_i32 s7, 0x8000
	s_cselect_b32 s10, s7, s6
	s_ashr_i32 s11, s10, 31
	s_lshl_b64 s[10:11], s[10:11], 12
	v_lshl_add_u64 v[0:1], v[24:25], 0, s[10:11]
	s_add_i32 s101, s6, 0xffffc000
	s_lshr_b32 s101, s101, 12
	s_add_i32 s101, s101, 2
	s_ashr_i32 s100, s6, 13
	s_cmpk_lt_i32 s6, 0x4000
	s_cselect_b32 s100, s100, s101
	v_readlane_b32 s101, v255, 11
	s_nop 1
	s_add_i32 s100, s100, s101
	s_mul_i32 s100, s100, 9
	s_ashr_i32 s101, s100, 31
	s_lshl_b64 s[100:101], s[100:101], 12
	v_lshl_add_u64 v[60:61], v[30:31], 0, s[100:101]
	s_mov_b64 s[100:101], 0x6000
	v_lshl_add_u64 v[62:63], v[60:61], 0, s[100:101]
	s_mov_b64 s[100:101], 0x7000
	v_lshl_add_u64 v[64:65], v[60:61], 0, s[100:101]
	global_load_dwordx4 v[68:71], v[26:27], off
	global_load_dwordx4 v[72:75], v[28:29], off
	global_load_dwordx4 v[76:79], v[62:63], off
	global_load_dwordx4 v[80:83], v[64:65], off
	global_load_dwordx4 v[84:87], v[26:27], off offset:1024
	global_load_dwordx4 v[88:91], v[28:29], off offset:1024
	global_load_dwordx4 v[92:95], v[62:63], off offset:1024
	global_load_dwordx4 v[96:99], v[64:65], off offset:1024
	global_load_dwordx4 v[100:103], v[26:27], off offset:2048
	global_load_dwordx4 v[104:107], v[28:29], off offset:2048
	global_load_dwordx4 v[108:111], v[62:63], off offset:2048
	global_load_dwordx4 v[112:115], v[64:65], off offset:2048
	global_load_dwordx4 v[116:119], v[26:27], off offset:3072
	global_load_dwordx4 v[120:123], v[28:29], off offset:3072
	global_load_dwordx4 v[124:127], v[62:63], off offset:3072
	global_load_dwordx4 v[128:131], v[64:65], off offset:3072
	global_load_dwordx4 v[16:19], v[0:1], off nt
	global_load_dwordx4 v[12:15], v[0:1], off offset:1024 nt
	global_load_dwordx4 v[8:11], v[0:1], off offset:2048 nt
	s_nop 0
	global_load_dwordx4 v[0:3], v[0:1], off offset:3072 nt
	v_pk_add_f32 v[42:43], v[38:39], v[20:21]
	s_mov_b32 s8, 0x800000
	v_pk_add_f32 v[42:43], v[40:41], v[42:43]
	s_nop 0
	v_pk_add_f32 v[42:43], v[22:23], v[42:43]
	s_nop 0
	v_add_f32_e32 v43, 0, v43
	v_add_f32_e32 v44, v42, v43
	v_pk_add_f32 v[42:43], v[34:35], v[4:5]
	s_nop 0
	v_pk_add_f32 v[42:43], v[36:37], v[42:43]
	s_nop 0
	v_pk_add_f32 v[42:43], v[6:7], v[42:43]
	s_nop 0
	v_add_f32_e32 v43, v43, v44
	v_add_f32_e32 v42, v42, v43
	s_nop 1
	v_add_f32_dpp v42, v42, v42 quad_perm:[1,0,3,2] row_mask:0xf bank_mask:0xf bound_ctrl:1
	s_nop 1
	v_add_f32_dpp v42, v42, v42 quad_perm:[2,3,0,1] row_mask:0xf bank_mask:0xf bound_ctrl:1
	s_nop 1
	v_add_f32_dpp v42, v42, v42 row_half_mirror row_mask:0xf bank_mask:0xf bound_ctrl:1
	s_nop 1
	v_add_f32_dpp v42, v42, v42 row_mirror row_mask:0xf bank_mask:0xf bound_ctrl:1
	s_nop 0
	v_readlane_b32 s12, v42, 16
	v_readlane_b32 s13, v42, 48
	v_readlane_b32 s10, v42, 0
	v_readlane_b32 s11, v42, 32
	v_mov_b32_e32 v42, s12
	v_mov_b32_e32 v43, s13
	v_pk_add_f32 v[42:43], s[10:11], v[42:43]
	s_nop 0
	v_add_f32_e32 v43, v42, v43
	v_fmac_f32_e32 v21, 0xba800000, v43
	v_fmac_f32_e32 v20, 0xba800000, v43
	v_fmac_f32_e32 v39, 0xba800000, v43
	v_fmac_f32_e32 v38, 0xba800000, v43
	v_mov_b32_e32 v46, v21
	v_mov_b32_e32 v47, v20
	v_fmac_f32_e32 v41, 0xba800000, v43
	v_fmac_f32_e32 v40, 0xba800000, v43
	v_mov_b32_e32 v44, v39
	v_mov_b32_e32 v45, v38
	v_pk_mul_f32 v[46:47], v[46:47], v[46:47]
	v_fmac_f32_e32 v23, 0xba800000, v43
	v_fmac_f32_e32 v22, 0xba800000, v43
	v_pk_fma_f32 v[44:45], v[44:45], v[44:45], v[46:47]
	v_mov_b32_e32 v46, v41
	v_mov_b32_e32 v47, v40
	v_pk_fma_f32 v[44:45], v[46:47], v[46:47], v[44:45]
	v_mov_b32_e32 v46, v23
	v_mov_b32_e32 v47, v22
	v_fmac_f32_e32 v5, 0xba800000, v43
	v_fmac_f32_e32 v4, 0xba800000, v43
	v_pk_fma_f32 v[44:45], v[46:47], v[46:47], v[44:45]
	v_fmac_f32_e32 v35, 0xba800000, v43
	v_fmac_f32_e32 v34, 0xba800000, v43
	v_pk_mul_f32 v[46:47], v[4:5], v[4:5]
	v_fmac_f32_e32 v37, 0xba800000, v43
	v_fmac_f32_e32 v36, 0xba800000, v43
	v_pk_fma_f32 v[46:47], v[34:35], v[34:35], v[46:47]
	v_fmac_f32_e32 v7, 0xba800000, v43
	v_fmac_f32_e32 v6, 0xba800000, v43
	v_pk_fma_f32 v[46:47], v[36:37], v[36:37], v[46:47]
	v_add_f32_e32 v42, v44, v45
	v_pk_fma_f32 v[46:47], v[6:7], v[6:7], v[46:47]
	s_nop 0
	v_add_f32_e32 v42, v47, v42
	v_add_f32_e32 v42, v46, v42
	s_nop 1
	v_add_f32_dpp v42, v42, v42 quad_perm:[1,0,3,2] row_mask:0xf bank_mask:0xf bound_ctrl:1
	s_nop 1
	v_add_f32_dpp v42, v42, v42 quad_perm:[2,3,0,1] row_mask:0xf bank_mask:0xf bound_ctrl:1
	s_nop 1
	v_add_f32_dpp v42, v42, v42 row_half_mirror row_mask:0xf bank_mask:0xf bound_ctrl:1
	s_nop 1
	v_add_f32_dpp v42, v42, v42 row_mirror row_mask:0xf bank_mask:0xf bound_ctrl:1
	s_nop 0
	v_readlane_b32 s12, v42, 16
	v_readlane_b32 s13, v42, 48
	v_readlane_b32 s10, v42, 0
	v_readlane_b32 s11, v42, 32
	v_mov_b32_e32 v44, s12
	v_mov_b32_e32 v45, s13
	v_pk_add_f32 v[44:45], s[10:11], v[44:45]
	s_nop 0
	v_add_f32_e32 v42, v44, v45
	v_fmamk_f32 v42, v42, 0x3a800000, v232
	v_mul_f32_e32 v44, 0x4b800000, v42
	v_cmp_gt_f32_e32 vcc, s8, v42
	s_nop 1
	v_cndmask_b32_e32 v42, v42, v44, vcc
	v_rsq_f32_e32 v42, v42
	s_nop 0
	v_mul_f32_e32 v44, 0x45800000, v42
	v_cndmask_b32_e32 v42, v42, v44, vcc
	s_and_saveexec_b64 s[12:13], s[38:39]
	s_cbranch_execz .LBB0_1623
	s_add_u32 s10, s92, s0
	v_mul_f32_e32 v44, 0x3a800000, v43
	s_addc_u32 s11, s93, s1
	v_mov_b32_e32 v45, v42
	global_store_dwordx2 v51, v[44:45], s[10:11]
	s_branch .LBB0_1623

.LBB0_1910:
	s_add_i32 s11, s26, s82
	s_cmpk_gt_i32 s11, 0x7fff
	s_cselect_b64 s[12:13], -1, 0
	s_cmp_lt_i32 s11, 0x8000
	s_cselect_b32 s14, s11, s26
	s_ashr_i32 s15, s14, 31
	s_lshl_b64 s[14:15], s[14:15], 12
	v_lshl_add_u64 v[0:1], v[28:29], 0, s[14:15]
	global_load_dwordx4 v[12:15], v[0:1], off nt
	global_load_dwordx4 v[8:11], v[0:1], off offset:1024 nt
	global_load_dwordx4 v[4:7], v[0:1], off offset:2048 nt
	s_nop 0
	global_load_dwordx4 v[0:3], v[0:1], off offset:3072 nt
	v_pk_add_f32 v[24:25], v[46:47], v[20:21]
	s_mov_b32 s8, 0x800000
	v_pk_add_f32 v[24:25], v[48:49], v[24:25]
	s_nop 0
	v_pk_add_f32 v[24:25], v[22:23], v[24:25]
	s_nop 0
	v_add_f32_e32 v25, 0, v25
	v_add_f32_e32 v26, v24, v25
	v_pk_add_f32 v[24:25], v[40:41], v[16:17]
	s_nop 0
	v_pk_add_f32 v[24:25], v[42:43], v[24:25]
	s_nop 0
	v_pk_add_f32 v[24:25], v[18:19], v[24:25]
	s_nop 0
	v_add_f32_e32 v25, v25, v26
	v_add_f32_e32 v24, v24, v25
	s_nop 1
	v_add_f32_dpp v24, v24, v24 quad_perm:[1,0,3,2] row_mask:0xf bank_mask:0xf bound_ctrl:1
	s_nop 1
	v_add_f32_dpp v24, v24, v24 quad_perm:[2,3,0,1] row_mask:0xf bank_mask:0xf bound_ctrl:1
	s_nop 1
	v_add_f32_dpp v24, v24, v24 row_half_mirror row_mask:0xf bank_mask:0xf bound_ctrl:1
	s_nop 1
	v_add_f32_dpp v24, v24, v24 row_mirror row_mask:0xf bank_mask:0xf bound_ctrl:1
	s_nop 0
	v_readlane_b32 s16, v24, 16
	v_readlane_b32 s17, v24, 48
	v_readlane_b32 s14, v24, 0
	v_readlane_b32 s15, v24, 32
	v_mov_b32_e32 v24, s16
	v_mov_b32_e32 v25, s17
	v_pk_add_f32 v[24:25], s[14:15], v[24:25]
	s_nop 0
	v_add_f32_e32 v24, v24, v25
	v_fmac_f32_e32 v21, 0xba800000, v24
	v_fmac_f32_e32 v20, 0xba800000, v24
	v_fmac_f32_e32 v47, 0xba800000, v24
	v_fmac_f32_e32 v46, 0xba800000, v24
	v_mov_b32_e32 v44, v21
	v_mov_b32_e32 v45, v20
	v_fmac_f32_e32 v49, 0xba800000, v24
	v_fmac_f32_e32 v48, 0xba800000, v24
	v_mov_b32_e32 v26, v47
	v_mov_b32_e32 v27, v46
	v_pk_mul_f32 v[44:45], v[44:45], v[44:45]
	v_fmac_f32_e32 v23, 0xba800000, v24
	v_fmac_f32_e32 v22, 0xba800000, v24
	v_pk_fma_f32 v[26:27], v[26:27], v[26:27], v[44:45]
	v_mov_b32_e32 v44, v49
	v_mov_b32_e32 v45, v48
	v_pk_fma_f32 v[26:27], v[44:45], v[44:45], v[26:27]
	v_mov_b32_e32 v44, v23
	v_mov_b32_e32 v45, v22
	v_fmac_f32_e32 v17, 0xba800000, v24
	v_fmac_f32_e32 v16, 0xba800000, v24
	v_pk_fma_f32 v[26:27], v[44:45], v[44:45], v[26:27]
	v_fmac_f32_e32 v41, 0xba800000, v24
	v_fmac_f32_e32 v40, 0xba800000, v24
	v_pk_mul_f32 v[44:45], v[16:17], v[16:17]
	v_fmac_f32_e32 v43, 0xba800000, v24
	v_fmac_f32_e32 v42, 0xba800000, v24
	v_pk_fma_f32 v[44:45], v[40:41], v[40:41], v[44:45]
	v_fmac_f32_e32 v19, 0xba800000, v24
	v_fmac_f32_e32 v18, 0xba800000, v24
	v_pk_fma_f32 v[44:45], v[42:43], v[42:43], v[44:45]
	v_add_f32_e32 v25, v26, v27
	v_pk_fma_f32 v[44:45], v[18:19], v[18:19], v[44:45]
	s_nop 0
	v_add_f32_e32 v25, v45, v25
	v_add_f32_e32 v25, v44, v25
	s_nop 1
	v_add_f32_dpp v25, v25, v25 quad_perm:[1,0,3,2] row_mask:0xf bank_mask:0xf bound_ctrl:1
	s_nop 1
	v_add_f32_dpp v25, v25, v25 quad_perm:[2,3,0,1] row_mask:0xf bank_mask:0xf bound_ctrl:1
	s_nop 1
	v_add_f32_dpp v25, v25, v25 row_half_mirror row_mask:0xf bank_mask:0xf bound_ctrl:1
	s_nop 1
	v_add_f32_dpp v25, v25, v25 row_mirror row_mask:0xf bank_mask:0xf bound_ctrl:1
	s_nop 0
	v_readlane_b32 s16, v25, 16
	v_readlane_b32 s17, v25, 48
	v_readlane_b32 s14, v25, 0
	v_readlane_b32 s15, v25, 32
	v_mov_b32_e32 v26, s16
	v_mov_b32_e32 v27, s17
	v_pk_add_f32 v[26:27], s[14:15], v[26:27]
	s_nop 0
	v_add_f32_e32 v25, v26, v27
	v_fmamk_f32 v25, v25, 0x3a800000, v232
	v_mul_f32_e32 v26, 0x4b800000, v25
	v_cmp_gt_f32_e32 vcc, s8, v25
	s_nop 1
	v_cndmask_b32_e32 v25, v25, v26, vcc
	v_rsq_f32_e32 v25, v25
	s_nop 0
	v_mul_f32_e32 v26, 0x45800000, v25
	v_cndmask_b32_e32 v44, v25, v26, vcc
	s_and_saveexec_b64 s[34:35], s[2:3]
	s_cbranch_execz .LBB0_1912
	s_add_u32 s14, s92, s1
	v_mul_f32_e32 v24, 0x3a800000, v24
	s_addc_u32 s15, s93, s10
	v_mov_b32_e32 v25, v44
	global_store_dwordx2 v51, v[24:25], s[14:15]

.LBB0_1934:
	s_add_i32 s10, s12, s82
	s_cmpk_gt_i32 s10, 0x7fff
	s_cselect_b64 s[6:7], -1, 0
	s_cmp_lt_i32 s10, 0x8000
	s_cselect_b32 s14, s10, s12
	s_ashr_i32 s15, s14, 31
	s_lshl_b64 s[14:15], s[14:15], 12
	v_lshl_add_u64 v[0:1], v[24:25], 0, s[14:15]
	s_add_i32 s101, s12, 0xffffc000
	s_lshr_b32 s101, s101, 12
	s_add_i32 s101, s101, 2
	s_ashr_i32 s100, s12, 13
	s_cmpk_lt_i32 s12, 0x4000
	s_cselect_b32 s100, s100, s101
	v_readlane_b32 s101, v255, 11
	s_nop 1
	s_add_i32 s100, s100, s101
	s_mul_i32 s100, s100, 9
	s_ashr_i32 s101, s100, 31
	s_lshl_b64 s[100:101], s[100:101], 12
	v_lshl_add_u64 v[60:61], v[30:31], 0, s[100:101]
	s_mov_b64 s[100:101], 0x3000
	v_lshl_add_u64 v[62:63], v[60:61], 0, s[100:101]
	s_mov_b64 s[100:101], 0x4000
	v_lshl_add_u64 v[64:65], v[60:61], 0, s[100:101]
	global_load_dwordx4 v[68:71], v[26:27], off
	global_load_dwordx4 v[72:75], v[28:29], off
	global_load_dwordx4 v[76:79], v[62:63], off
	global_load_dwordx4 v[80:83], v[64:65], off
	global_load_dwordx4 v[84:87], v[26:27], off offset:1024
	global_load_dwordx4 v[88:91], v[28:29], off offset:1024
	global_load_dwordx4 v[92:95], v[62:63], off offset:1024
	global_load_dwordx4 v[96:99], v[64:65], off offset:1024
	global_load_dwordx4 v[100:103], v[26:27], off offset:2048
	global_load_dwordx4 v[104:107], v[28:29], off offset:2048
	global_load_dwordx4 v[108:111], v[62:63], off offset:2048
	global_load_dwordx4 v[112:115], v[64:65], off offset:2048
	global_load_dwordx4 v[116:119], v[26:27], off offset:3072
	global_load_dwordx4 v[120:123], v[28:29], off offset:3072
	global_load_dwordx4 v[124:127], v[62:63], off offset:3072
	global_load_dwordx4 v[128:131], v[64:65], off offset:3072
	global_load_dwordx4 v[16:19], v[0:1], off nt
	global_load_dwordx4 v[12:15], v[0:1], off offset:1024 nt
	global_load_dwordx4 v[8:11], v[0:1], off offset:2048 nt
	s_nop 0
	global_load_dwordx4 v[0:3], v[0:1], off offset:3072 nt
	v_pk_add_f32 v[42:43], v[38:39], v[20:21]
	s_mov_b32 s8, 0x800000
	v_pk_add_f32 v[42:43], v[40:41], v[42:43]
	s_nop 0
	v_pk_add_f32 v[42:43], v[22:23], v[42:43]
	s_nop 0
	v_add_f32_e32 v43, 0, v43
	v_add_f32_e32 v44, v42, v43
	v_pk_add_f32 v[42:43], v[34:35], v[4:5]
	s_nop 0
	v_pk_add_f32 v[42:43], v[36:37], v[42:43]
	s_nop 0
	v_pk_add_f32 v[42:43], v[6:7], v[42:43]
	s_nop 0
	v_add_f32_e32 v43, v43, v44
	v_add_f32_e32 v42, v42, v43
	s_nop 1
	v_add_f32_dpp v42, v42, v42 quad_perm:[1,0,3,2] row_mask:0xf bank_mask:0xf bound_ctrl:1
	s_nop 1
	v_add_f32_dpp v42, v42, v42 quad_perm:[2,3,0,1] row_mask:0xf bank_mask:0xf bound_ctrl:1
	s_nop 1
	v_add_f32_dpp v42, v42, v42 row_half_mirror row_mask:0xf bank_mask:0xf bound_ctrl:1
	s_nop 1
	v_add_f32_dpp v42, v42, v42 row_mirror row_mask:0xf bank_mask:0xf bound_ctrl:1
	s_nop 0
	v_readlane_b32 s11, v42, 16
	v_readlane_b32 s13, v42, 48
	v_readlane_b32 s14, v42, 0
	v_readlane_b32 s15, v42, 32
	v_mov_b32_e32 v42, s11
	v_mov_b32_e32 v43, s13
	v_pk_add_f32 v[42:43], s[14:15], v[42:43]
	s_nop 0
	v_add_f32_e32 v43, v42, v43
	v_fmac_f32_e32 v21, 0xba800000, v43
	v_fmac_f32_e32 v20, 0xba800000, v43
	v_fmac_f32_e32 v39, 0xba800000, v43
	v_fmac_f32_e32 v38, 0xba800000, v43
	v_mov_b32_e32 v46, v21
	v_mov_b32_e32 v47, v20
	v_fmac_f32_e32 v41, 0xba800000, v43
	v_fmac_f32_e32 v40, 0xba800000, v43
	v_mov_b32_e32 v44, v39
	v_mov_b32_e32 v45, v38
	v_pk_mul_f32 v[46:47], v[46:47], v[46:47]
	v_fmac_f32_e32 v23, 0xba800000, v43
	v_fmac_f32_e32 v22, 0xba800000, v43
	v_pk_fma_f32 v[44:45], v[44:45], v[44:45], v[46:47]
	v_mov_b32_e32 v46, v41
	v_mov_b32_e32 v47, v40
	v_pk_fma_f32 v[44:45], v[46:47], v[46:47], v[44:45]
	v_mov_b32_e32 v46, v23
	v_mov_b32_e32 v47, v22
	v_fmac_f32_e32 v5, 0xba800000, v43
	v_fmac_f32_e32 v4, 0xba800000, v43
	v_pk_fma_f32 v[44:45], v[46:47], v[46:47], v[44:45]
	v_fmac_f32_e32 v35, 0xba800000, v43
	v_fmac_f32_e32 v34, 0xba800000, v43
	v_pk_mul_f32 v[46:47], v[4:5], v[4:5]
	v_fmac_f32_e32 v37, 0xba800000, v43
	v_fmac_f32_e32 v36, 0xba800000, v43
	v_pk_fma_f32 v[46:47], v[34:35], v[34:35], v[46:47]
	v_fmac_f32_e32 v7, 0xba800000, v43
	v_fmac_f32_e32 v6, 0xba800000, v43
	v_pk_fma_f32 v[46:47], v[36:37], v[36:37], v[46:47]
	v_add_f32_e32 v42, v44, v45
	v_pk_fma_f32 v[46:47], v[6:7], v[6:7], v[46:47]
	s_nop 0
	v_add_f32_e32 v42, v47, v42
	v_add_f32_e32 v42, v46, v42
	s_nop 1
	v_add_f32_dpp v42, v42, v42 quad_perm:[1,0,3,2] row_mask:0xf bank_mask:0xf bound_ctrl:1
	s_nop 1
	v_add_f32_dpp v42, v42, v42 quad_perm:[2,3,0,1] row_mask:0xf bank_mask:0xf bound_ctrl:1
	s_nop 1
	v_add_f32_dpp v42, v42, v42 row_half_mirror row_mask:0xf bank_mask:0xf bound_ctrl:1
	s_nop 1
	v_add_f32_dpp v42, v42, v42 row_mirror row_mask:0xf bank_mask:0xf bound_ctrl:1
	s_nop 0
	v_readlane_b32 s11, v42, 16
	v_readlane_b32 s13, v42, 48
	v_readlane_b32 s14, v42, 0
	v_readlane_b32 s15, v42, 32
	v_mov_b32_e32 v44, s11
	v_mov_b32_e32 v45, s13
	v_pk_add_f32 v[44:45], s[14:15], v[44:45]
	s_nop 0
	v_add_f32_e32 v42, v44, v45
	v_fmamk_f32 v42, v42, 0x3a800000, v232
	v_mul_f32_e32 v44, 0x4b800000, v42
	v_cmp_gt_f32_e32 vcc, s8, v42
	s_nop 1
	v_cndmask_b32_e32 v42, v42, v44, vcc
	v_rsq_f32_e32 v42, v42
	s_nop 0
	v_mul_f32_e32 v44, 0x45800000, v42
	v_cndmask_b32_e32 v42, v42, v44, vcc
	s_and_saveexec_b64 s[26:27], s[38:39]
	s_cbranch_execz .LBB0_1933
	s_add_u32 s14, s92, s0
	v_mul_f32_e32 v44, 0x3a800000, v43
	s_addc_u32 s15, s93, s1
	v_mov_b32_e32 v45, v42
	global_store_dwordx2 v51, v[44:45], s[14:15]
	s_branch .LBB0_1933
